# attn2/attn3: accumulator start-value copies read one register pair instead of a 16-register broadcast (14 fewer VALU per 2 tiles)
# speedup vs baseline: 1.0052x; 1.0023x over previous
.LBB0_449:
	s_add_i32 s19, s16, 3
	s_add_i32 s18, s17, 1
	s_cmp_lg_u32 s17, 2
	s_cselect_b32 s18, s18, 0
	s_mul_i32 s27, s18, 0x2e00
	v_add_u32_e32 v2, s27, v37
	v_add_u32_e32 v130, v2, v154
	ds_read_b128 v[122:125], v130
	ds_read_b128 v[126:129], v130 offset:32
	v_xor_b32_e32 v38, 0x80000000, v147
	v_mov_b32_e32 v39, v38
	v_mov_b64_e32 v[54:55], v[38:39]
	v_mov_b64_e32 v[56:57], v[38:39]
	v_mov_b64_e32 v[58:59], v[38:39]
	v_mov_b64_e32 v[60:61], v[38:39]
	v_mov_b64_e32 v[62:63], v[38:39]
	v_mov_b64_e32 v[64:65], v[38:39]
	v_mov_b64_e32 v[66:67], v[38:39]
	v_mov_b64_e32 v[68:69], v[38:39]
	ds_read_b128 v[40:43], v130 offset:64
	ds_read_b128 v[44:47], v130 offset:96
	s_waitcnt lgkmcnt(3)
	v_mfma_f32_32x32x16_bf16 v[54:69], v[122:125], v[86:89], v[54:69]
	v_min_i32_e32 v39, s19, v145
	v_mad_u64_u32 v[48:49], s[38:39], v39, s67, v[178:179]
	v_mul_hi_u32_u24_e32 v51, v138, v39
	v_mul_u32_u24_e32 v50, v138, v39
	global_load_dwordx4 v[122:125], v[48:49], off
	s_waitcnt lgkmcnt(2)
	v_mfma_f32_32x32x16_bf16 v[54:69], v[126:129], v[90:93], v[54:69]
	s_waitcnt lgkmcnt(1)
	v_mfma_f32_32x32x16_bf16 v[54:69], v[40:43], v[94:97], v[54:69]
	ds_read_b128 v[40:43], v130 offset:128
	s_waitcnt lgkmcnt(1)
	v_mfma_f32_32x32x16_bf16 v[54:69], v[44:47], v[98:101], v[54:69]
	v_mul_hi_u32_u24_e32 v45, v136, v39
	v_mul_u32_u24_e32 v44, v136, v39
	v_lshl_add_u64 v[46:47], v[50:51], 1, v[180:181]
	v_lshl_add_u64 v[48:49], v[44:45], 1, v[182:183]
	global_load_dwordx4 v[126:129], v[46:47], off
	ds_read_b128 v[44:47], v130 offset:160
	global_load_dwordx4 v[130:133], v[48:49], off
	s_waitcnt lgkmcnt(1)
	v_mfma_f32_32x32x16_bf16 v[54:69], v[40:43], v[102:105], v[54:69]
	v_max3_f32 v39, v70, s69, v71
	v_max3_f32 v39, v39, v72, v73
	v_max3_f32 v39, v39, v74, v75
	v_max3_f32 v39, v39, v76, v77
	v_max3_f32 v39, v39, v78, v79
	v_max3_f32 v39, v39, v80, v81
	v_max3_f32 v39, v39, v82, v83
	s_waitcnt lgkmcnt(0)
	v_mfma_f32_32x32x16_bf16 v[54:69], v[44:47], v[106:109], v[54:69]
	v_max3_f32 v39, v39, v84, v85
	v_cmp_lt_f32_e32 vcc, s22, v39
	s_cbranch_vccz .LBB0_451
	ds_bpermute_b32 v38, v156, v39
	s_waitcnt lgkmcnt(0)
	v_max3_f32 v38, v39, v38, 0
	v_exp_f32_e64 v40, -v38
	v_add_f32_e32 v147, v147, v38
	v_pk_add_f32 v[70:71], v[70:71], v[38:39] op_sel_hi:[1,0] neg_lo:[0,1] neg_hi:[0,1]
	v_pk_add_f32 v[72:73], v[72:73], v[38:39] op_sel_hi:[1,0] neg_lo:[0,1] neg_hi:[0,1]
	v_pk_add_f32 v[74:75], v[74:75], v[38:39] op_sel_hi:[1,0] neg_lo:[0,1] neg_hi:[0,1]
	v_pk_add_f32 v[76:77], v[76:77], v[38:39] op_sel_hi:[1,0] neg_lo:[0,1] neg_hi:[0,1]
	v_pk_add_f32 v[78:79], v[78:79], v[38:39] op_sel_hi:[1,0] neg_lo:[0,1] neg_hi:[0,1]
	v_pk_add_f32 v[80:81], v[80:81], v[38:39] op_sel_hi:[1,0] neg_lo:[0,1] neg_hi:[0,1]
	v_mul_f32_e32 v149, v149, v40
	v_pk_add_f32 v[82:83], v[82:83], v[38:39] op_sel_hi:[1,0] neg_lo:[0,1] neg_hi:[0,1]
	v_pk_add_f32 v[84:85], v[84:85], v[38:39] op_sel_hi:[1,0] neg_lo:[0,1] neg_hi:[0,1]
	v_pk_mul_f32 v[34:35], v[34:35], v[40:41] op_sel_hi:[1,0]
	v_pk_mul_f32 v[32:33], v[32:33], v[40:41] op_sel_hi:[1,0]
	v_pk_mul_f32 v[30:31], v[30:31], v[40:41] op_sel_hi:[1,0]
	v_pk_mul_f32 v[28:29], v[28:29], v[40:41] op_sel_hi:[1,0]
	v_pk_mul_f32 v[26:27], v[26:27], v[40:41] op_sel_hi:[1,0]
	v_pk_mul_f32 v[24:25], v[24:25], v[40:41] op_sel_hi:[1,0]
	v_pk_mul_f32 v[22:23], v[22:23], v[40:41] op_sel_hi:[1,0]
	v_pk_mul_f32 v[20:21], v[20:21], v[40:41] op_sel_hi:[1,0]
	v_pk_mul_f32 v[18:19], v[18:19], v[40:41] op_sel_hi:[1,0]
	v_pk_mul_f32 v[16:17], v[16:17], v[40:41] op_sel_hi:[1,0]
	v_pk_mul_f32 v[14:15], v[14:15], v[40:41] op_sel_hi:[1,0]
	v_pk_mul_f32 v[12:13], v[12:13], v[40:41] op_sel_hi:[1,0]
	v_pk_mul_f32 v[10:11], v[10:11], v[40:41] op_sel_hi:[1,0]
	v_pk_mul_f32 v[8:9], v[8:9], v[40:41] op_sel_hi:[1,0]
	v_pk_mul_f32 v[6:7], v[6:7], v[40:41] op_sel_hi:[1,0]
	v_pk_mul_f32 v[4:5], v[4:5], v[40:41] op_sel_hi:[1,0]
	v_sub_f32_e32 v69, v69, v38
	v_sub_f32_e32 v68, v68, v38
	v_sub_f32_e32 v67, v67, v38
	v_sub_f32_e32 v66, v66, v38
	v_sub_f32_e32 v65, v65, v38
	v_sub_f32_e32 v64, v64, v38
	v_sub_f32_e32 v63, v63, v38
	v_sub_f32_e32 v62, v62, v38
	v_sub_f32_e32 v61, v61, v38
	v_sub_f32_e32 v60, v60, v38
	v_sub_f32_e32 v59, v59, v38
	v_sub_f32_e32 v58, v58, v38
	v_sub_f32_e32 v57, v57, v38
	v_sub_f32_e32 v56, v56, v38
	v_sub_f32_e32 v55, v55, v38
	v_sub_f32_e32 v54, v54, v38
	v_xor_b32_e32 v38, 0x80000000, v147

.LBB0_546:
	s_mul_i32 s3, s16, 0x4c00
	v_add_u32_e32 v171, s3, v154
	v_add_u32_e32 v142, v171, v188
	ds_read_b128 v[134:137], v142
	ds_read_b128 v[138:141], v142 offset:32
	v_xor_b32_e32 v70, 0x80000000, v167
	v_mov_b32_e32 v71, v70
	v_mov_b64_e32 v[86:87], v[70:71]
	v_mov_b64_e32 v[88:89], v[70:71]
	v_mov_b64_e32 v[90:91], v[70:71]
	v_mov_b64_e32 v[92:93], v[70:71]
	v_mov_b64_e32 v[94:95], v[70:71]
	v_mov_b64_e32 v[96:97], v[70:71]
	v_mov_b64_e32 v[98:99], v[70:71]
	v_mov_b64_e32 v[100:101], v[70:71]
	s_add_i32 s3, s2, -1
	v_min_i32_e32 v2, s3, v165
	s_waitcnt vmcnt(1) lgkmcnt(1)
	v_mfma_f32_32x32x16_bf16 v[86:101], v[134:137], v[114:117], v[86:101]
	v_lshlrev_b64 v[76:77], 12, v[2:3]
	v_lshl_add_u64 v[78:79], v[180:181], 0, v[76:77]
	v_lshl_add_u64 v[76:77], v[182:183], 0, v[76:77]
	ds_read_b128 v[72:75], v142 offset:64
	global_load_dwordx4 v[134:137], v[78:79], off
	s_waitcnt lgkmcnt(1)
	v_mfma_f32_32x32x16_bf16 v[86:101], v[138:141], v[102:105], v[86:101]
	global_load_dwordx4 v[138:141], v[76:77], off
	v_lshlrev_b64 v[76:77], 13, v[2:3]
	v_lshl_add_u64 v[80:81], v[184:185], 0, v[76:77]
	v_lshl_add_u64 v[82:83], v[186:187], 0, v[76:77]
	ds_read_b128 v[76:79], v142 offset:96
	global_load_dwordx4 v[146:149], v[80:81], off
	global_load_dwordx4 v[142:145], v[82:83], off
	s_waitcnt lgkmcnt(1)
	v_mfma_f32_32x32x16_bf16 v[86:101], v[72:75], v[106:109], v[86:101]
	s_waitcnt vmcnt(4) lgkmcnt(0)
	v_mfma_f32_32x32x16_bf16 v[86:101], v[76:79], v[118:121], v[86:101]
	s_nop 11
	v_max3_f32 v2, v86, s69, v87
	v_max3_f32 v2, v2, v88, v89
	v_max3_f32 v2, v2, v90, v91
	v_max3_f32 v2, v2, v92, v93
	v_max3_f32 v2, v2, v94, v95
	v_max3_f32 v2, v2, v96, v97
	v_max3_f32 v2, v2, v98, v99
	v_max3_f32 v2, v2, v100, v101
	v_cmp_lt_f32_e32 vcc, s22, v2
	s_cbranch_vccz .LBB0_548
	ds_bpermute_b32 v70, v1, v2
	s_waitcnt lgkmcnt(0)
	v_max3_f32 v2, v2, v70, 0
	v_exp_f32_e64 v70, -v2
	v_add_f32_e32 v167, v167, v2
	v_pk_add_f32 v[86:87], v[86:87], v[2:3] op_sel_hi:[1,0] neg_lo:[0,1] neg_hi:[0,1]
	v_pk_add_f32 v[88:89], v[88:89], v[2:3] op_sel_hi:[1,0] neg_lo:[0,1] neg_hi:[0,1]
	v_pk_add_f32 v[90:91], v[90:91], v[2:3] op_sel_hi:[1,0] neg_lo:[0,1] neg_hi:[0,1]
	v_pk_add_f32 v[92:93], v[92:93], v[2:3] op_sel_hi:[1,0] neg_lo:[0,1] neg_hi:[0,1]
	v_pk_add_f32 v[94:95], v[94:95], v[2:3] op_sel_hi:[1,0] neg_lo:[0,1] neg_hi:[0,1]
	v_pk_add_f32 v[96:97], v[96:97], v[2:3] op_sel_hi:[1,0] neg_lo:[0,1] neg_hi:[0,1]
	v_mul_f32_e32 v169, v169, v70
	v_pk_add_f32 v[98:99], v[98:99], v[2:3] op_sel_hi:[1,0] neg_lo:[0,1] neg_hi:[0,1]
	v_pk_add_f32 v[100:101], v[100:101], v[2:3] op_sel_hi:[1,0] neg_lo:[0,1] neg_hi:[0,1]
	v_pk_mul_f32 v[18:19], v[18:19], v[70:71] op_sel_hi:[1,0]
	v_pk_mul_f32 v[16:17], v[16:17], v[70:71] op_sel_hi:[1,0]
	v_pk_mul_f32 v[14:15], v[14:15], v[70:71] op_sel_hi:[1,0]
	v_pk_mul_f32 v[12:13], v[12:13], v[70:71] op_sel_hi:[1,0]
	v_pk_mul_f32 v[10:11], v[10:11], v[70:71] op_sel_hi:[1,0]
	v_pk_mul_f32 v[8:9], v[8:9], v[70:71] op_sel_hi:[1,0]
	v_pk_mul_f32 v[6:7], v[6:7], v[70:71] op_sel_hi:[1,0]
	v_pk_mul_f32 v[4:5], v[4:5], v[70:71] op_sel_hi:[1,0]
	v_pk_mul_f32 v[34:35], v[34:35], v[70:71] op_sel_hi:[1,0]
	v_pk_mul_f32 v[32:33], v[32:33], v[70:71] op_sel_hi:[1,0]
	v_pk_mul_f32 v[30:31], v[30:31], v[70:71] op_sel_hi:[1,0]
	v_pk_mul_f32 v[28:29], v[28:29], v[70:71] op_sel_hi:[1,0]
	v_pk_mul_f32 v[26:27], v[26:27], v[70:71] op_sel_hi:[1,0]
	v_pk_mul_f32 v[24:25], v[24:25], v[70:71] op_sel_hi:[1,0]
	v_pk_mul_f32 v[22:23], v[22:23], v[70:71] op_sel_hi:[1,0]
	v_pk_mul_f32 v[20:21], v[20:21], v[70:71] op_sel_hi:[1,0]
	v_pk_mul_f32 v[52:53], v[52:53], v[70:71] op_sel_hi:[1,0]
	v_pk_mul_f32 v[50:51], v[50:51], v[70:71] op_sel_hi:[1,0]
	v_pk_mul_f32 v[48:49], v[48:49], v[70:71] op_sel_hi:[1,0]
	v_pk_mul_f32 v[46:47], v[46:47], v[70:71] op_sel_hi:[1,0]
	v_pk_mul_f32 v[44:45], v[44:45], v[70:71] op_sel_hi:[1,0]
	v_pk_mul_f32 v[42:43], v[42:43], v[70:71] op_sel_hi:[1,0]
	v_pk_mul_f32 v[40:41], v[40:41], v[70:71] op_sel_hi:[1,0]
	v_pk_mul_f32 v[38:39], v[38:39], v[70:71] op_sel_hi:[1,0]
	v_pk_mul_f32 v[68:69], v[68:69], v[70:71] op_sel_hi:[1,0]
	v_pk_mul_f32 v[66:67], v[66:67], v[70:71] op_sel_hi:[1,0]
	v_pk_mul_f32 v[64:65], v[64:65], v[70:71] op_sel_hi:[1,0]
	v_pk_mul_f32 v[62:63], v[62:63], v[70:71] op_sel_hi:[1,0]
	v_pk_mul_f32 v[60:61], v[60:61], v[70:71] op_sel_hi:[1,0]
	v_pk_mul_f32 v[58:59], v[58:59], v[70:71] op_sel_hi:[1,0]
	v_pk_mul_f32 v[56:57], v[56:57], v[70:71] op_sel_hi:[1,0]
	v_pk_mul_f32 v[54:55], v[54:55], v[70:71] op_sel_hi:[1,0]
	v_xor_b32_e32 v70, 0x80000000, v167
